# variant of v37: P3 per-CU order MLA short unit -> gate units -> MLA long unit (gates spread over the first half of the phase)
# baseline (speedup 1.0000x reference)
.LBB0_724:
	s_mul_i32 s0, s14, 0xc0
	s_ashr_i32 s1, s0, 31
	s_lshl_b64 s[0:1], s[0:1], 1
	s_add_u32 s8, s45, s0
	s_addc_u32 s9, s46, s1
	s_add_u32 s14, s47, s0
	s_addc_u32 s15, s48, s1
	s_add_u32 s16, s49, s12
	s_addc_u32 s17, s50, s13
	s_add_u32 s18, s35, s18
	s_addc_u32 s19, s44, s19
	s_add_u32 s20, s16, 0x200000
	s_addc_u32 s21, s17, 0
	v_readlane_b32 vcc_lo, v236, 15
	s_nop 3
	s_cmp_eq_u32 vcc_lo, 0
	s_cselect_b64 s[6:7], 0, -1
	s_branch .LBB0_726
